# seam: first release poll issued ahead of the code-prefetch loads so its result is not queued behind them
# speedup vs baseline: 1.0007x; 1.0007x over previous
.Lxb_pf_0:
	buffer_inv sc1
	v_readlane_b32 s16, v252, 5
	s_nop 3
	s_and_b32 s16, s16, 15
	s_lshl_b32 s16, s16, 8
	s_add_u32 s14, s14, s16
	s_addc_u32 s15, s15, 0
	s_mov_b32 s16, 0
	global_load_dword v5, v6, s[14:15] sc1
	s_getpc_b64 s[18:19]
	s_mov_b64 s[22:23], exec
	s_mov_b64 exec, -1
	v_mbcnt_lo_u32_b32 v254, -1, 0
	v_mbcnt_hi_u32_b32 v254, -1, v254
	v_lshlrev_b32_e32 v254, 7, v254
	global_load_dword v255, v254, s[18:19]
	s_add_u32 s18, s18, 0x2000
	s_addc_u32 s19, s19, 0
	global_load_dword v255, v254, s[18:19]
	s_add_u32 s18, s18, 0x2000
	s_addc_u32 s19, s19, 0
	global_load_dword v255, v254, s[18:19]
	s_add_u32 s18, s18, 0x2000
	s_addc_u32 s19, s19, 0
	global_load_dword v255, v254, s[18:19]
	s_mov_b64 exec, s[22:23]
	s_waitcnt vmcnt(4)
	v_cmp_ge_u32_e32 vcc, v5, v4
	s_cbranch_vccnz .Lxb_done_0
	s_branch .Lxb_spin_0

.Lxb_pf_13:
	buffer_inv sc1
	v_readlane_b32 s16, v252, 5
	s_nop 3
	s_and_b32 s16, s16, 15
	s_lshl_b32 s16, s16, 8
	s_add_u32 s14, s14, s16
	s_addc_u32 s15, s15, 0
	s_mov_b32 s16, 0
	global_load_dword v5, v6, s[14:15] sc1
	s_getpc_b64 s[18:19]
	s_mov_b64 s[22:23], exec
	s_mov_b64 exec, -1
	v_mbcnt_lo_u32_b32 v254, -1, 0
	v_mbcnt_hi_u32_b32 v254, -1, v254
	v_lshlrev_b32_e32 v254, 7, v254
	global_load_dword v255, v254, s[18:19]
	s_add_u32 s18, s18, 0x2000
	s_addc_u32 s19, s19, 0
	global_load_dword v255, v254, s[18:19]
	s_mov_b64 exec, s[22:23]
	s_waitcnt vmcnt(2)
	v_cmp_ge_u32_e32 vcc, v5, v4
	s_cbranch_vccnz .Lxb_done_13
	s_branch .Lxb_spin_13

.Lxb_pf_14:
	buffer_inv sc1
	v_readlane_b32 s16, v252, 5
	s_nop 3
	s_and_b32 s16, s16, 15
	s_lshl_b32 s16, s16, 8
	s_add_u32 s14, s14, s16
	s_addc_u32 s15, s15, 0
	s_mov_b32 s16, 0
	global_load_dword v5, v6, s[14:15] sc1
	s_getpc_b64 s[18:19]
	s_mov_b64 s[22:23], exec
	s_mov_b64 exec, -1
	v_mbcnt_lo_u32_b32 v254, -1, 0
	v_mbcnt_hi_u32_b32 v254, -1, v254
	v_lshlrev_b32_e32 v254, 7, v254
	global_load_dword v255, v254, s[18:19]
	s_mov_b64 exec, s[22:23]
	s_waitcnt vmcnt(1)
	v_cmp_ge_u32_e32 vcc, v5, v4
	s_cbranch_vccnz .Lxb_done_14
	s_branch .Lxb_spin_14
